# G1 MFMA segment: lgkmcnt waits merged to one per fragment group (10 instead of 19 s_waitcnt inside the segment)
# speedup vs baseline: 1.0033x; 1.0033x over previous
; __device__ __forceinline__ void gemm_core_big(const bf16_t* __restrict__ A, int lda, const bf16_t* __restrict__ Bt, int ldb,
;                                               int K, f32x4 (&acc)[8][4], char* smem) {
;     ...
;   for (int kt = 0; kt < nk; ++kt) {
;     __syncthreads();
; #pragma unroll
;     for (int i = 0; i < 8; ++i) *(u32x4*)(wA + 32 * i * LDS_STRIDE) = ra[i];
; #pragma unroll
;     for (int i = 0; i < 4; ++i) *(u32x4*)(wB + 32 * i * LDS_STRIDE) = rb[i];
;     __syncthreads();
;     {
;       const int k1 = min(kt + 1, nk - 1) << 6;
; #pragma unroll
;       for (int i = 0; i < 8; ++i) ra[i] = *(const u32x4*)(ap + (size_t)(32 * i) * lda + k1);
; #pragma unroll
;       for (int i = 0; i < 4; ++i) rb[i] = *(const u32x4*)(bp + (size_t)(32 * i) * ldb + k1);
;     }
; #pragma unroll
;     for (int ks = 0; ks < 2; ++ks) {
;       const int fo = ks ? fo1 : fo0;
;       bf16x8 bfr[4];
; #pragma unroll
;       for (int j = 0; j < 4; ++j) bfr[j] = *(const bf16x8*)(cB + j * 16 * LDS_STRIDE + fo);
; #pragma unroll
;       for (int i = 0; i < 8; ++i) {
;         const bf16x8 af = *(const bf16x8*)(cA + i * 16 * LDS_STRIDE + fo);
; #pragma unroll
;         for (int j = 0; j < 4; ++j)
;           acc[i][j] = __builtin_amdgcn_mfma_f32_16x16x32_bf16(bfr[j], af, acc[i][j], 0, 0, 0);
;       }
;     }
.LBB0_711:
	s_setprio 0
	s_barrier
	s_add_i32 m0, s15, 0x8000
	s_nop 0
	global_load_lds_dwordx4 v224, s[30:31]
	s_mov_b32 m0, s15
	s_nop 0
	global_load_lds_dwordx4 v224, s[28:29]
	s_add_i32 m0, s15, 0x1000
	s_nop 0
	global_load_lds_dwordx4 v225, s[28:29]
	s_add_i32 m0, s15, 0x2000
	s_nop 0
	global_load_lds_dwordx4 v226, s[28:29]
	s_add_i32 m0, s15, 0x3000
	s_nop 0
	global_load_lds_dwordx4 v227, s[28:29]
	s_add_i32 m0, s15, 0x4000
	s_nop 0
	global_load_lds_dwordx4 v228, s[28:29]
	s_add_i32 m0, s15, 0x5000
	s_nop 0
	global_load_lds_dwordx4 v229, s[28:29]
	s_add_i32 m0, s15, 0x6000
	s_nop 0
	global_load_lds_dwordx4 v230, s[28:29]
	s_add_i32 m0, s15, 0x7000
	s_nop 0
	global_load_lds_dwordx4 v231, s[28:29]
	s_add_i32 m0, s15, 0x9000
	s_nop 0
	global_load_lds_dwordx4 v225, s[30:31]
	s_add_i32 m0, s15, 0xa000
	s_nop 0
	global_load_lds_dwordx4 v226, s[30:31]
	s_add_i32 m0, s15, 0xb000
	s_nop 0
	global_load_lds_dwordx4 v227, s[30:31]
	s_add_u32 s28, s28, 0x80
	s_addc_u32 s29, s29, 0
	s_add_u32 s30, s30, 0x80
	s_addc_u32 s31, s31, 0
	s_add_i32 s26, s26, 1
	s_lshl_b32 s18, s13, 7
	s_cmp_lg_u32 s26, 17
	s_waitcnt vmcnt(0)
	s_barrier
	ds_read_b128 v[134:137], v140 offset:32768
	ds_read_b128 v[148:151], v141 offset:0
	ds_read_b128 v[144:147], v140 offset:34816
	ds_read_b128 v[156:159], v140 offset:36864
	ds_read_b128 v[160:163], v140 offset:38912
	ds_read_b128 v[152:155], v141 offset:2048
	ds_read_b128 v[216:219], v141 offset:4096
	ds_read_b128 v[220:223], v141 offset:6144
	ds_read_b128 v[164:167], v141 offset:8192
	ds_read_b128 v[168:171], v141 offset:10240
	s_setprio 1
	s_waitcnt lgkmcnt(8)
	v_mfma_f32_16x16x32_bf16 v[128:131], v[134:137], v[148:151], v[128:131]
	s_waitcnt lgkmcnt(5)
	v_mfma_f32_16x16x32_bf16 v[124:127], v[144:147], v[148:151], v[124:127]
	v_mfma_f32_16x16x32_bf16 v[120:123], v[156:159], v[148:151], v[120:123]
	v_mfma_f32_16x16x32_bf16 v[116:119], v[160:163], v[148:151], v[116:119]
	s_waitcnt lgkmcnt(4)
	v_mfma_f32_16x16x32_bf16 v[112:115], v[134:137], v[152:155], v[112:115]
	v_mfma_f32_16x16x32_bf16 v[108:111], v[144:147], v[152:155], v[108:111]
	v_mfma_f32_16x16x32_bf16 v[104:107], v[156:159], v[152:155], v[104:107]
	v_mfma_f32_16x16x32_bf16 v[100:103], v[160:163], v[152:155], v[100:103]
	ds_read_b128 v[172:175], v141 offset:12288
	ds_read_b128 v[188:191], v141 offset:14336
	s_waitcnt lgkmcnt(4)
	v_mfma_f32_16x16x32_bf16 v[96:99], v[134:137], v[216:219], v[96:99]
	v_mfma_f32_16x16x32_bf16 v[92:95], v[144:147], v[216:219], v[92:95]
	v_mfma_f32_16x16x32_bf16 v[88:91], v[156:159], v[216:219], v[88:91]
	v_mfma_f32_16x16x32_bf16 v[84:87], v[160:163], v[216:219], v[84:87]
	v_mfma_f32_16x16x32_bf16 v[80:83], v[134:137], v[220:223], v[80:83]
	v_mfma_f32_16x16x32_bf16 v[76:79], v[144:147], v[220:223], v[76:79]
	v_mfma_f32_16x16x32_bf16 v[72:75], v[156:159], v[220:223], v[72:75]
	v_mfma_f32_16x16x32_bf16 v[68:71], v[160:163], v[220:223], v[68:71]
	ds_read_b128 v[148:151], v143 offset:0
	ds_read_b128 v[152:155], v143 offset:2048
	ds_read_b128 v[200:203], v142 offset:32768
	ds_read_b128 v[204:207], v142 offset:34816
	ds_read_b128 v[208:211], v142 offset:36864
	ds_read_b128 v[212:215], v142 offset:38912
	s_waitcnt lgkmcnt(8)
	v_mfma_f32_16x16x32_bf16 v[64:67], v[134:137], v[164:167], v[64:67]
	v_mfma_f32_16x16x32_bf16 v[60:63], v[144:147], v[164:167], v[60:63]
	v_mfma_f32_16x16x32_bf16 v[56:59], v[156:159], v[164:167], v[56:59]
	v_mfma_f32_16x16x32_bf16 v[52:55], v[160:163], v[164:167], v[52:55]
	v_mfma_f32_16x16x32_bf16 v[48:51], v[134:137], v[168:171], v[48:51]
	v_mfma_f32_16x16x32_bf16 v[44:47], v[144:147], v[168:171], v[44:47]
	v_mfma_f32_16x16x32_bf16 v[40:43], v[156:159], v[168:171], v[40:43]
	v_mfma_f32_16x16x32_bf16 v[36:39], v[160:163], v[168:171], v[36:39]
	ds_read_b128 v[216:219], v143 offset:4096
	ds_read_b128 v[220:223], v143 offset:6144
	s_waitcnt lgkmcnt(8)
	v_mfma_f32_16x16x32_bf16 v[32:35], v[134:137], v[172:175], v[32:35]
	v_mfma_f32_16x16x32_bf16 v[24:27], v[144:147], v[172:175], v[24:27]
	v_mfma_f32_16x16x32_bf16 v[20:23], v[156:159], v[172:175], v[20:23]
	v_mfma_f32_16x16x32_bf16 v[16:19], v[160:163], v[172:175], v[16:19]
	v_mfma_f32_16x16x32_bf16 v[12:15], v[134:137], v[188:191], v[12:15]
	v_mfma_f32_16x16x32_bf16 v[8:11], v[144:147], v[188:191], v[8:11]
	v_mfma_f32_16x16x32_bf16 v[4:7], v[156:159], v[188:191], v[4:7]
	v_mfma_f32_16x16x32_bf16 v[28:31], v[160:163], v[188:191], v[28:31]
	ds_read_b128 v[164:167], v143 offset:8192
	ds_read_b128 v[168:171], v143 offset:10240
	s_waitcnt lgkmcnt(4)
	v_mfma_f32_16x16x32_bf16 v[128:131], v[200:203], v[148:151], v[128:131]
	v_mfma_f32_16x16x32_bf16 v[124:127], v[204:207], v[148:151], v[124:127]
	v_mfma_f32_16x16x32_bf16 v[120:123], v[208:211], v[148:151], v[120:123]
	v_mfma_f32_16x16x32_bf16 v[116:119], v[212:215], v[148:151], v[116:119]
	v_mfma_f32_16x16x32_bf16 v[112:115], v[200:203], v[152:155], v[112:115]
	v_mfma_f32_16x16x32_bf16 v[108:111], v[204:207], v[152:155], v[108:111]
	v_mfma_f32_16x16x32_bf16 v[104:107], v[208:211], v[152:155], v[104:107]
	v_mfma_f32_16x16x32_bf16 v[100:103], v[212:215], v[152:155], v[100:103]
	ds_read_b128 v[172:175], v143 offset:12288
	ds_read_b128 v[188:191], v143 offset:14336
	s_waitcnt lgkmcnt(4)
	v_mfma_f32_16x16x32_bf16 v[96:99], v[200:203], v[216:219], v[96:99]
	v_mfma_f32_16x16x32_bf16 v[92:95], v[204:207], v[216:219], v[92:95]
	v_mfma_f32_16x16x32_bf16 v[88:91], v[208:211], v[216:219], v[88:91]
	v_mfma_f32_16x16x32_bf16 v[84:87], v[212:215], v[216:219], v[84:87]
	v_mfma_f32_16x16x32_bf16 v[80:83], v[200:203], v[220:223], v[80:83]
	v_mfma_f32_16x16x32_bf16 v[76:79], v[204:207], v[220:223], v[76:79]
	v_mfma_f32_16x16x32_bf16 v[72:75], v[208:211], v[220:223], v[72:75]
	v_mfma_f32_16x16x32_bf16 v[68:71], v[212:215], v[220:223], v[68:71]
	s_waitcnt lgkmcnt(2)
	v_mfma_f32_16x16x32_bf16 v[64:67], v[200:203], v[164:167], v[64:67]
	v_mfma_f32_16x16x32_bf16 v[60:63], v[204:207], v[164:167], v[60:63]
	v_mfma_f32_16x16x32_bf16 v[56:59], v[208:211], v[164:167], v[56:59]
	v_mfma_f32_16x16x32_bf16 v[52:55], v[212:215], v[164:167], v[52:55]
	v_mfma_f32_16x16x32_bf16 v[48:51], v[200:203], v[168:171], v[48:51]
	v_mfma_f32_16x16x32_bf16 v[44:47], v[204:207], v[168:171], v[44:47]
	v_mfma_f32_16x16x32_bf16 v[40:43], v[208:211], v[168:171], v[40:43]
	v_mfma_f32_16x16x32_bf16 v[36:39], v[212:215], v[168:171], v[36:39]
	s_waitcnt lgkmcnt(0)
	v_mfma_f32_16x16x32_bf16 v[32:35], v[200:203], v[172:175], v[32:35]
	v_mfma_f32_16x16x32_bf16 v[24:27], v[204:207], v[172:175], v[24:27]
	v_mfma_f32_16x16x32_bf16 v[20:23], v[208:211], v[172:175], v[20:23]
	v_mfma_f32_16x16x32_bf16 v[16:19], v[212:215], v[172:175], v[16:19]
	v_mfma_f32_16x16x32_bf16 v[12:15], v[200:203], v[188:191], v[12:15]
	v_mfma_f32_16x16x32_bf16 v[8:11], v[204:207], v[188:191], v[8:11]
	v_mfma_f32_16x16x32_bf16 v[4:7], v[208:211], v[188:191], v[4:7]
	v_mfma_f32_16x16x32_bf16 v[28:31], v[212:215], v[188:191], v[28:31]
	s_cbranch_scc1 .LBB0_711
; __device__ __forceinline__ unsigned pack2(float a, float b) { return (unsigned)f2bf(a) | ((unsigned)f2bf(b) << 16); }
; __device__ __forceinline__ void phase_gemm_in(const Params& p, char* smem) {
;     ...
;     bf16_t* dst; int ldd, ncol0;
;     if (nt < PRE_W / 128) { dst = PRE; ldd = PRE_W; ncol0 = nt * 128; }
;     else { dst = POST; ldd = POST_W; ncol0 = (nt - PRE_W / 128) * 128; }
; #pragma unroll
;     for (int i = 0; i < 8; ++i) {
;       const int m = mt * 256 + wm * 128 + i * 16 + (lane & 15);
; #pragma unroll
;       for (int j = 0; j < 4; ++j) {
;         const int n = ncol0 + wn * 64 + j * 16 + (lane >> 4) * 4;
;         uint2 o;
;         o.x = pack2(acc[i][j][0], acc[i][j][1]);
;         o.y = pack2(acc[i][j][2], acc[i][j][3]);
;         *(uint2*)(dst + (size_t)m * ldd + n) = o;
;       }
;     }
	s_setprio 0
	s_lshl_b32 s13, s14, 7
	s_add_i32 s15, s13, 0xffffef00
	s_cmp_lt_i32 s14, 34
	s_mov_b32 s14, 0x4100000
	s_cselect_b32 s18, s14, 0xcb20000
	s_movk_i32 s0, 0x1200
	s_cselect_b32 s15, s13, s15
	s_cselect_b32 s14, 0x1100, s0
	v_lshl_add_u32 v2, s12, 8, v138
	s_add_u32 s12, s10, s18
	v_or_b32_e32 v0, s15, v139
	s_addc_u32 s13, s11, 0
	s_lshl_b32 s18, s14, 4
	v_ashrrev_i32_e32 v1, 31, v0
	v_lshlrev_b64 v[0:1], 1, v[0:1]
	v_bfe_u32 v136, v178, 4, 1
	v_mul_u32_u24_e32 v136, 24, v136
	v_add_u32_e32 v0, v0, v136
	v_bfe_u32 v136, v178, 3, 1
	v_lshlrev_b32_e32 v136, 6, v136
	v_add_u32_e32 v0, v0, v136
	v_and_b32_e32 v2, 0xfffffff7, v2
	v_mad_i64_i32 v[132:133], s[26:27], s14, v2, 0
	v_lshl_add_u64 v[132:133], v[132:133], 1, s[12:13]
	v_lshl_add_u64 v[132:133], v[132:133], 0, v[0:1]
	v_lshl_add_u64 v[134:135], v[132:133], 0, s[18:19]
	v_cvt_pk_bf16_f32 v144, v128, v129
	v_cvt_pk_bf16_f32 v146, v124, v125
	v_cvt_pk_bf16_f32 v145, v130, v131
	v_cvt_pk_bf16_f32 v147, v126, v127
	v_cvt_pk_bf16_f32 v148, v120, v121
	v_cvt_pk_bf16_f32 v150, v116, v117
	v_cvt_pk_bf16_f32 v149, v122, v123
	v_cvt_pk_bf16_f32 v151, v118, v119
	v_permlane16_swap_b32_e32 v144, v146
	v_permlane16_swap_b32_e32 v145, v147
	v_permlane16_swap_b32_e32 v148, v150
	v_permlane16_swap_b32_e32 v149, v151
	v_mov_b32_e32 v152, v144
	v_mov_b32_e32 v153, v145
	v_mov_b32_e32 v154, v146
	v_mov_b32_e32 v155, v147
	v_mov_b32_dpp v144, v148 row_ror:8 row_mask:0xf bank_mask:0xc
	v_mov_b32_dpp v145, v149 row_ror:8 row_mask:0xf bank_mask:0xc
	v_mov_b32_dpp v146, v150 row_ror:8 row_mask:0xf bank_mask:0xc
	v_mov_b32_dpp v147, v151 row_ror:8 row_mask:0xf bank_mask:0xc
	v_mov_b32_dpp v148, v152 row_ror:8 row_mask:0xf bank_mask:0x3
	v_mov_b32_dpp v149, v153 row_ror:8 row_mask:0xf bank_mask:0x3
	v_mov_b32_dpp v150, v154 row_ror:8 row_mask:0xf bank_mask:0x3
	v_mov_b32_dpp v151, v155 row_ror:8 row_mask:0xf bank_mask:0x3
	global_store_dwordx4 v[132:133], v[144:147], off nt
	global_store_dwordx4 v[134:135], v[148:151], off nt
	v_or_b32_e32 v172, 0x10, v2
	v_mad_i64_i32 v[168:169], s[26:27], s14, v172, 0
	v_lshl_add_u64 v[168:169], v[168:169], 1, s[12:13]
	v_lshl_add_u64 v[168:169], v[168:169], 0, v[0:1]
	v_lshl_add_u64 v[170:171], v[168:169], 0, s[18:19]
	v_cvt_pk_bf16_f32 v156, v112, v113
	v_cvt_pk_bf16_f32 v158, v108, v109
	v_cvt_pk_bf16_f32 v157, v114, v115
	v_cvt_pk_bf16_f32 v159, v110, v111
	v_cvt_pk_bf16_f32 v160, v104, v105
	v_cvt_pk_bf16_f32 v162, v100, v101
	v_cvt_pk_bf16_f32 v161, v106, v107
	v_cvt_pk_bf16_f32 v163, v102, v103
	v_permlane16_swap_b32_e32 v156, v158
	v_permlane16_swap_b32_e32 v157, v159
	v_permlane16_swap_b32_e32 v160, v162
	v_permlane16_swap_b32_e32 v161, v163
	v_mov_b32_e32 v164, v156
	v_mov_b32_e32 v165, v157
	v_mov_b32_e32 v166, v158
	v_mov_b32_e32 v167, v159
	v_mov_b32_dpp v156, v160 row_ror:8 row_mask:0xf bank_mask:0xc
	v_mov_b32_dpp v157, v161 row_ror:8 row_mask:0xf bank_mask:0xc
	v_mov_b32_dpp v158, v162 row_ror:8 row_mask:0xf bank_mask:0xc
	v_mov_b32_dpp v159, v163 row_ror:8 row_mask:0xf bank_mask:0xc
	v_mov_b32_dpp v160, v164 row_ror:8 row_mask:0xf bank_mask:0x3
	v_mov_b32_dpp v161, v165 row_ror:8 row_mask:0xf bank_mask:0x3
	v_mov_b32_dpp v162, v166 row_ror:8 row_mask:0xf bank_mask:0x3
	v_mov_b32_dpp v163, v167 row_ror:8 row_mask:0xf bank_mask:0x3
	global_store_dwordx4 v[168:169], v[156:159], off nt
	global_store_dwordx4 v[170:171], v[160:163], off nt
	v_or_b32_e32 v172, 0x20, v2
	v_mad_i64_i32 v[132:133], s[26:27], s14, v172, 0
	v_lshl_add_u64 v[132:133], v[132:133], 1, s[12:13]
	v_lshl_add_u64 v[132:133], v[132:133], 0, v[0:1]
	v_lshl_add_u64 v[134:135], v[132:133], 0, s[18:19]
	v_cvt_pk_bf16_f32 v144, v96, v97
	v_cvt_pk_bf16_f32 v146, v92, v93
	v_cvt_pk_bf16_f32 v145, v98, v99
	v_cvt_pk_bf16_f32 v147, v94, v95
	v_cvt_pk_bf16_f32 v148, v88, v89
	v_cvt_pk_bf16_f32 v150, v84, v85
	v_cvt_pk_bf16_f32 v149, v90, v91
	v_cvt_pk_bf16_f32 v151, v86, v87
	v_permlane16_swap_b32_e32 v144, v146
	v_permlane16_swap_b32_e32 v145, v147
	v_permlane16_swap_b32_e32 v148, v150
	v_permlane16_swap_b32_e32 v149, v151
	v_mov_b32_e32 v152, v144
	v_mov_b32_e32 v153, v145
	v_mov_b32_e32 v154, v146
	v_mov_b32_e32 v155, v147
	v_mov_b32_dpp v144, v148 row_ror:8 row_mask:0xf bank_mask:0xc
	v_mov_b32_dpp v145, v149 row_ror:8 row_mask:0xf bank_mask:0xc
	v_mov_b32_dpp v146, v150 row_ror:8 row_mask:0xf bank_mask:0xc
	v_mov_b32_dpp v147, v151 row_ror:8 row_mask:0xf bank_mask:0xc
	v_mov_b32_dpp v148, v152 row_ror:8 row_mask:0xf bank_mask:0x3
	v_mov_b32_dpp v149, v153 row_ror:8 row_mask:0xf bank_mask:0x3
	v_mov_b32_dpp v150, v154 row_ror:8 row_mask:0xf bank_mask:0x3
	v_mov_b32_dpp v151, v155 row_ror:8 row_mask:0xf bank_mask:0x3
	global_store_dwordx4 v[132:133], v[144:147], off nt
	global_store_dwordx4 v[134:135], v[148:151], off nt
	v_or_b32_e32 v172, 0x30, v2
	v_mad_i64_i32 v[168:169], s[26:27], s14, v172, 0
	v_lshl_add_u64 v[168:169], v[168:169], 1, s[12:13]
	v_lshl_add_u64 v[168:169], v[168:169], 0, v[0:1]
	v_lshl_add_u64 v[170:171], v[168:169], 0, s[18:19]
	v_cvt_pk_bf16_f32 v156, v80, v81
	v_cvt_pk_bf16_f32 v158, v76, v77
	v_cvt_pk_bf16_f32 v157, v82, v83
	v_cvt_pk_bf16_f32 v159, v78, v79
	v_cvt_pk_bf16_f32 v160, v72, v73
	v_cvt_pk_bf16_f32 v162, v68, v69
	v_cvt_pk_bf16_f32 v161, v74, v75
	v_cvt_pk_bf16_f32 v163, v70, v71
	v_permlane16_swap_b32_e32 v156, v158
	v_permlane16_swap_b32_e32 v157, v159
	v_permlane16_swap_b32_e32 v160, v162
	v_permlane16_swap_b32_e32 v161, v163
	v_mov_b32_e32 v164, v156
	v_mov_b32_e32 v165, v157
	v_mov_b32_e32 v166, v158
	v_mov_b32_e32 v167, v159
	v_mov_b32_dpp v156, v160 row_ror:8 row_mask:0xf bank_mask:0xc
	v_mov_b32_dpp v157, v161 row_ror:8 row_mask:0xf bank_mask:0xc
; __device__ __forceinline__ unsigned pack2(float a, float b) { return (unsigned)f2bf(a) | ((unsigned)f2bf(b) << 16); }
; __device__ __forceinline__ void phase_gemm_in(const Params& p, char* smem) {
;     ...
; #pragma unroll
;     for (int i = 0; i < 8; ++i) {
;       const int m = mt * 256 + wm * 128 + i * 16 + (lane & 15);
; #pragma unroll
;       for (int j = 0; j < 4; ++j) {
;         const int n = ncol0 + wn * 64 + j * 16 + (lane >> 4) * 4;
;         uint2 o;
;         o.x = pack2(acc[i][j][0], acc[i][j][1]);
;         o.y = pack2(acc[i][j][2], acc[i][j][3]);
;         *(uint2*)(dst + (size_t)m * ldd + n) = o;
;       }
;     }
	v_mov_b32_dpp v158, v162 row_ror:8 row_mask:0xf bank_mask:0xc
	v_mov_b32_dpp v159, v163 row_ror:8 row_mask:0xf bank_mask:0xc
	v_mov_b32_dpp v160, v164 row_ror:8 row_mask:0xf bank_mask:0x3
	v_mov_b32_dpp v161, v165 row_ror:8 row_mask:0xf bank_mask:0x3
	v_mov_b32_dpp v162, v166 row_ror:8 row_mask:0xf bank_mask:0x3
	v_mov_b32_dpp v163, v167 row_ror:8 row_mask:0xf bank_mask:0x3
	global_store_dwordx4 v[168:169], v[156:159], off nt
	global_store_dwordx4 v[170:171], v[160:163], off nt
	v_or_b32_e32 v172, 0x40, v2
	v_mad_i64_i32 v[132:133], s[26:27], s14, v172, 0
	v_lshl_add_u64 v[132:133], v[132:133], 1, s[12:13]
	v_lshl_add_u64 v[132:133], v[132:133], 0, v[0:1]
	v_lshl_add_u64 v[134:135], v[132:133], 0, s[18:19]
	v_cvt_pk_bf16_f32 v144, v64, v65
	v_cvt_pk_bf16_f32 v146, v60, v61
	v_cvt_pk_bf16_f32 v145, v66, v67
	v_cvt_pk_bf16_f32 v147, v62, v63
	v_cvt_pk_bf16_f32 v148, v56, v57
	v_cvt_pk_bf16_f32 v150, v52, v53
	v_cvt_pk_bf16_f32 v149, v58, v59
	v_cvt_pk_bf16_f32 v151, v54, v55
	v_permlane16_swap_b32_e32 v144, v146
	v_permlane16_swap_b32_e32 v145, v147
	v_permlane16_swap_b32_e32 v148, v150
	v_permlane16_swap_b32_e32 v149, v151
	v_mov_b32_e32 v152, v144
	v_mov_b32_e32 v153, v145
	v_mov_b32_e32 v154, v146
	v_mov_b32_e32 v155, v147
	v_mov_b32_dpp v144, v148 row_ror:8 row_mask:0xf bank_mask:0xc
	v_mov_b32_dpp v145, v149 row_ror:8 row_mask:0xf bank_mask:0xc
	v_mov_b32_dpp v146, v150 row_ror:8 row_mask:0xf bank_mask:0xc
	v_mov_b32_dpp v147, v151 row_ror:8 row_mask:0xf bank_mask:0xc
	v_mov_b32_dpp v148, v152 row_ror:8 row_mask:0xf bank_mask:0x3
	v_mov_b32_dpp v149, v153 row_ror:8 row_mask:0xf bank_mask:0x3
	v_mov_b32_dpp v150, v154 row_ror:8 row_mask:0xf bank_mask:0x3
	v_mov_b32_dpp v151, v155 row_ror:8 row_mask:0xf bank_mask:0x3
	global_store_dwordx4 v[132:133], v[144:147], off nt
	global_store_dwordx4 v[134:135], v[148:151], off nt
	v_or_b32_e32 v172, 0x50, v2
	v_mad_i64_i32 v[168:169], s[26:27], s14, v172, 0
	v_lshl_add_u64 v[168:169], v[168:169], 1, s[12:13]
	v_lshl_add_u64 v[168:169], v[168:169], 0, v[0:1]
	v_lshl_add_u64 v[170:171], v[168:169], 0, s[18:19]
	v_cvt_pk_bf16_f32 v156, v48, v49
	v_cvt_pk_bf16_f32 v158, v44, v45
	v_cvt_pk_bf16_f32 v157, v50, v51
	v_cvt_pk_bf16_f32 v159, v46, v47
	v_cvt_pk_bf16_f32 v160, v40, v41
	v_cvt_pk_bf16_f32 v162, v36, v37
	v_cvt_pk_bf16_f32 v161, v42, v43
	v_cvt_pk_bf16_f32 v163, v38, v39
	v_permlane16_swap_b32_e32 v156, v158
	v_permlane16_swap_b32_e32 v157, v159
	v_permlane16_swap_b32_e32 v160, v162
	v_permlane16_swap_b32_e32 v161, v163
	v_mov_b32_e32 v164, v156
	v_mov_b32_e32 v165, v157
	v_mov_b32_e32 v166, v158
	v_mov_b32_e32 v167, v159
	v_mov_b32_dpp v156, v160 row_ror:8 row_mask:0xf bank_mask:0xc
	v_mov_b32_dpp v157, v161 row_ror:8 row_mask:0xf bank_mask:0xc
	v_mov_b32_dpp v158, v162 row_ror:8 row_mask:0xf bank_mask:0xc
	v_mov_b32_dpp v159, v163 row_ror:8 row_mask:0xf bank_mask:0xc
	v_mov_b32_dpp v160, v164 row_ror:8 row_mask:0xf bank_mask:0x3
	v_mov_b32_dpp v161, v165 row_ror:8 row_mask:0xf bank_mask:0x3
	v_mov_b32_dpp v162, v166 row_ror:8 row_mask:0xf bank_mask:0x3
	v_mov_b32_dpp v163, v167 row_ror:8 row_mask:0xf bank_mask:0x3
	global_store_dwordx4 v[168:169], v[156:159], off nt
	global_store_dwordx4 v[170:171], v[160:163], off nt
	v_or_b32_e32 v172, 0x60, v2
	v_mad_i64_i32 v[132:133], s[26:27], s14, v172, 0
	v_lshl_add_u64 v[132:133], v[132:133], 1, s[12:13]
	v_lshl_add_u64 v[132:133], v[132:133], 0, v[0:1]
	v_lshl_add_u64 v[134:135], v[132:133], 0, s[18:19]
	v_cvt_pk_bf16_f32 v144, v32, v33
	v_cvt_pk_bf16_f32 v146, v24, v25
	v_cvt_pk_bf16_f32 v145, v34, v35
	v_cvt_pk_bf16_f32 v147, v26, v27
	v_cvt_pk_bf16_f32 v148, v20, v21
	v_cvt_pk_bf16_f32 v150, v16, v17
	v_cvt_pk_bf16_f32 v149, v22, v23
	v_cvt_pk_bf16_f32 v151, v18, v19
	v_permlane16_swap_b32_e32 v144, v146
	v_permlane16_swap_b32_e32 v145, v147
	v_permlane16_swap_b32_e32 v148, v150
	v_permlane16_swap_b32_e32 v149, v151
	v_mov_b32_e32 v152, v144
	v_mov_b32_e32 v153, v145
	v_mov_b32_e32 v154, v146
	v_mov_b32_e32 v155, v147
	v_mov_b32_dpp v144, v148 row_ror:8 row_mask:0xf bank_mask:0xc
	v_mov_b32_dpp v145, v149 row_ror:8 row_mask:0xf bank_mask:0xc
	v_mov_b32_dpp v146, v150 row_ror:8 row_mask:0xf bank_mask:0xc
	v_mov_b32_dpp v147, v151 row_ror:8 row_mask:0xf bank_mask:0xc
	v_mov_b32_dpp v148, v152 row_ror:8 row_mask:0xf bank_mask:0x3
	v_mov_b32_dpp v149, v153 row_ror:8 row_mask:0xf bank_mask:0x3
	v_mov_b32_dpp v150, v154 row_ror:8 row_mask:0xf bank_mask:0x3
	v_mov_b32_dpp v151, v155 row_ror:8 row_mask:0xf bank_mask:0x3
	global_store_dwordx4 v[132:133], v[144:147], off nt
	global_store_dwordx4 v[134:135], v[148:151], off nt
	v_or_b32_e32 v172, 0x70, v2
	v_mad_i64_i32 v[168:169], s[26:27], s14, v172, 0
	v_lshl_add_u64 v[168:169], v[168:169], 1, s[12:13]
	v_lshl_add_u64 v[168:169], v[168:169], 0, v[0:1]
	v_lshl_add_u64 v[170:171], v[168:169], 0, s[18:19]
	v_cvt_pk_bf16_f32 v156, v12, v13
	v_cvt_pk_bf16_f32 v158, v8, v9
	v_cvt_pk_bf16_f32 v157, v14, v15
	v_cvt_pk_bf16_f32 v159, v10, v11
	v_cvt_pk_bf16_f32 v160, v4, v5
	v_cvt_pk_bf16_f32 v162, v28, v29
	v_cvt_pk_bf16_f32 v161, v6, v7
	v_cvt_pk_bf16_f32 v163, v30, v31
	v_permlane16_swap_b32_e32 v156, v158
	v_permlane16_swap_b32_e32 v157, v159
	v_permlane16_swap_b32_e32 v160, v162
	v_permlane16_swap_b32_e32 v161, v163
	v_mov_b32_e32 v164, v156
	v_mov_b32_e32 v165, v157
	v_mov_b32_e32 v166, v158
	v_mov_b32_e32 v167, v159
	v_mov_b32_dpp v156, v160 row_ror:8 row_mask:0xf bank_mask:0xc
	v_mov_b32_dpp v157, v161 row_ror:8 row_mask:0xf bank_mask:0xc
	v_mov_b32_dpp v158, v162 row_ror:8 row_mask:0xf bank_mask:0xc
	v_mov_b32_dpp v159, v163 row_ror:8 row_mask:0xf bank_mask:0xc
	v_mov_b32_dpp v160, v164 row_ror:8 row_mask:0xf bank_mask:0x3
	v_mov_b32_dpp v161, v165 row_ror:8 row_mask:0xf bank_mask:0x3
	v_mov_b32_dpp v162, v166 row_ror:8 row_mask:0xf bank_mask:0x3
	v_mov_b32_dpp v163, v167 row_ror:8 row_mask:0xf bank_mask:0x3
	global_store_dwordx4 v[168:169], v[156:159], off nt
	global_store_dwordx4 v[170:171], v[160:163], off nt
	s_add_i32 s23, s23, 1
	s_cmp_eq_u32 s23, s17
	s_cselect_b64 s[12:13], -1, 0
	s_mov_b32 s31, 0x18000
	s_branch .LBB0_708
